# packed f32 FMA for the GLA gate logits in both GLA item loops
# speedup vs baseline: 1.0043x; 1.0043x over previous
.LBB0_188:
	v_mov_b32_e32 v148, v204
	v_lshlrev_b32_e32 v128, 16, v52
	v_and_b32_e32 v129, 0xffff0000, v52
	v_lshlrev_b32_e32 v130, 16, v53
	v_and_b32_e32 v131, 0xffff0000, v53
	v_lshl_add_u32 v2, v148, 4, 0
	ds_write_b128 v2, v[128:131]
	v_mad_u64_u32 v[2:3], s[8:9], v148, -12, v[2:3]
	v_ashrrev_i32_e32 v3, 3, v148
	ds_write2st64_b32 v2, v59, v58 offset0:32 offset1:40
	ds_write2st64_b32 v2, v57, v56 offset0:48 offset1:56
	v_and_b32_e32 v2, 0x7f, v148
	v_lshlrev_b32_e32 v3, 1, v3
	v_readfirstlane_b32 s7, v148
	v_mul_u32_u24_e32 v2, 0x90, v2
	v_and_b32_e32 v3, 0xffffffe0, v3
	s_ashr_i32 s6, s7, 6
	v_add3_u32 v2, s92, v2, v3
	ds_write_b128 v2, v[44:47]
	ds_write_b128 v2, v[48:51] offset:16
	v_lshlrev_b32_e32 v2, 2, v148
	s_lshl_b32 s8, s6, 10
	v_and_b32_e32 v149, 0xfc, v2
	s_add_i32 s8, s8, 0
	v_add_u32_e32 v148, 0, v149
	v_mov_b32_e32 v150, s8
	v_lshlrev_b32_e32 v146, 16, v89
	v_lshlrev_b32_e32 v147, 16, v81
	v_lshlrev_b32_e32 v140, 16, v87
	v_lshlrev_b32_e32 v141, 16, v79
	v_lshlrev_b32_e32 v138, 16, v84
	v_lshlrev_b32_e32 v139, 16, v78
	v_lshlrev_b32_e32 v136, 16, v83
	v_lshlrev_b32_e32 v137, 16, v55
	v_lshlrev_b32_e32 v134, 16, v91
	v_lshlrev_b32_e32 v135, 16, v85
	v_lshlrev_b32_e32 v132, 16, v90
	v_lshlrev_b32_e32 v133, 16, v82
	v_lshlrev_b32_e32 v130, 16, v88
	v_lshlrev_b32_e32 v131, 16, v80
	v_lshlrev_b32_e32 v128, 16, v86
	v_lshlrev_b32_e32 v129, 16, v54
	s_waitcnt lgkmcnt(0)
	s_barrier
	ds_read2st64_b32 v[88:89], v148 offset0:32 offset1:33
	ds_read2st64_b32 v[84:85], v148 offset0:48 offset1:49
	ds_read2st64_b32 v[90:91], v148 offset0:34 offset1:35
	ds_read2st64_b32 v[86:87], v148 offset0:50 offset1:51
	ds_read2st64_b32 v[78:79], v148 offset0:36 offset1:37
	ds_read2st64_b32 v[58:59], v148 offset0:52 offset1:53
	ds_read2st64_b32 v[80:81], v148 offset0:38 offset1:39
	ds_read2st64_b32 v[82:83], v148 offset0:54 offset1:55
	ds_read2st64_b32 v[54:55], v148 offset0:40 offset1:41
	ds_read2st64_b32 v[50:51], v148 offset0:56 offset1:57
	ds_read2st64_b32 v[56:57], v148 offset0:42 offset1:43
	ds_read2st64_b32 v[52:53], v148 offset0:58 offset1:59
	ds_read2st64_b32 v[44:45], v148 offset0:44 offset1:45
	ds_read2st64_b32 v[2:3], v148 offset0:60 offset1:61
	ds_read2st64_b32 v[46:47], v148 offset0:46 offset1:47
	ds_read2st64_b32 v[48:49], v148 offset0:62 offset1:63
	s_mov_b32 s8, 0x3d800000
	s_and_b32 s7, s7, 0x3fffffc0
	s_lshl_b32 s7, s7, 2
	s_add_i32 s7, s7, 0
	s_ashr_i32 s28, s27, 6
	s_cmp_gt_i32 s6, 0
	s_cselect_b64 vcc, -1, 0
	s_cmp_lt_i32 s6, 0
	v_and_b32_e32 v124, 63, v126
	v_and_b32_e32 v123, 15, v126
	ds_read_b128 v[222:225], v150
	ds_read_b128 v[226:229], v150 offset:16
	ds_read_b128 v[230:233], v150 offset:32
	ds_read_b128 v[234:237], v150 offset:48
	ds_read_b128 v[238:241], v150 offset:64
	ds_read_b128 v[196:199], v150 offset:80
	ds_read_b128 v[200:203], v150 offset:96
	ds_read_b128 v[176:179], v150 offset:112
	s_waitcnt lgkmcnt(0)
	v_pk_mul_f32 v[180:181], v[222:223], v[88:89]
	v_pk_mul_f32 v[174:175], v[238:239], v[84:85]
	v_pk_mul_f32 v[242:243], v[224:225], v[90:91]
	v_pk_mul_f32 v[172:173], v[240:241], v[86:87]
	v_pk_fma_f32 v[180:181], v[226:227], v[78:79], v[180:181]
	v_pk_fma_f32 v[174:175], v[196:197], v[58:59], v[174:175]
	v_pk_fma_f32 v[242:243], v[228:229], v[80:81], v[242:243]
	v_pk_fma_f32 v[172:173], v[198:199], v[82:83], v[172:173]
	v_pk_fma_f32 v[180:181], v[230:231], v[54:55], v[180:181]
	v_pk_fma_f32 v[174:175], v[200:201], v[50:51], v[174:175]
	v_pk_fma_f32 v[242:243], v[232:233], v[56:57], v[242:243]
	v_pk_fma_f32 v[172:173], v[202:203], v[52:53], v[172:173]
	v_pk_fma_f32 v[180:181], v[234:235], v[44:45], v[180:181]
	v_pk_fma_f32 v[174:175], v[176:177], v[2:3], v[174:175]
	v_pk_fma_f32 v[242:243], v[236:237], v[46:47], v[242:243]
	v_pk_fma_f32 v[172:173], v[178:179], v[48:49], v[172:173]
	ds_read_b128 v[222:225], v150 offset:128
	ds_read_b128 v[226:229], v150 offset:144
	ds_read_b128 v[230:233], v150 offset:160
	ds_read_b128 v[234:237], v150 offset:176
	ds_read_b128 v[238:241], v150 offset:192
	ds_read_b128 v[196:199], v150 offset:208
	ds_read_b128 v[200:203], v150 offset:224
	ds_read_b128 v[176:179], v150 offset:240
	v_pk_add_f32 v[180:181], v[180:181], v[242:243]
	v_pk_add_f32 v[174:175], v[174:175], v[172:173]
	v_add_f32_e32 v180, v180, v181
	v_add_f32_e32 v174, v174, v175
	v_add_f32_e32 v180, v127, v180
	v_add_f32_e32 v174, v125, v174
	v_mul_f32_e64 v181, |v180|, s58
	v_mul_f32_e64 v175, |v174|, s58
	v_exp_f32_e32 v181, v181
	v_exp_f32_e32 v175, v175
	v_min_f32_e32 v180, 0, v180
	v_min_f32_e32 v174, 0, v174
	v_add_f32_e32 v181, 1.0, v181
	v_add_f32_e32 v175, 1.0, v175
	v_log_f32_e32 v181, v181
	v_log_f32_e32 v175, v175
	s_nop 0
	v_fma_f32 v151, v180, s82, -v181
	v_fma_f32 v159, v174, s82, -v175
	s_waitcnt lgkmcnt(0)
	v_pk_mul_f32 v[180:181], v[222:223], v[88:89]
	v_pk_mul_f32 v[174:175], v[238:239], v[84:85]
	v_pk_mul_f32 v[242:243], v[224:225], v[90:91]
	v_pk_mul_f32 v[172:173], v[240:241], v[86:87]
	v_pk_fma_f32 v[180:181], v[226:227], v[78:79], v[180:181]
	v_pk_fma_f32 v[174:175], v[196:197], v[58:59], v[174:175]
	v_pk_fma_f32 v[242:243], v[228:229], v[80:81], v[242:243]
	v_pk_fma_f32 v[172:173], v[198:199], v[82:83], v[172:173]
	v_pk_fma_f32 v[180:181], v[230:231], v[54:55], v[180:181]
	v_pk_fma_f32 v[174:175], v[200:201], v[50:51], v[174:175]
	v_pk_fma_f32 v[242:243], v[232:233], v[56:57], v[242:243]
	v_pk_fma_f32 v[172:173], v[202:203], v[52:53], v[172:173]
	v_pk_fma_f32 v[180:181], v[234:235], v[44:45], v[180:181]
	v_pk_fma_f32 v[174:175], v[176:177], v[2:3], v[174:175]
	v_pk_fma_f32 v[242:243], v[236:237], v[46:47], v[242:243]
	v_pk_fma_f32 v[172:173], v[178:179], v[48:49], v[172:173]
	ds_read_b128 v[222:225], v150 offset:256
	ds_read_b128 v[226:229], v150 offset:272
	ds_read_b128 v[230:233], v150 offset:288
	ds_read_b128 v[234:237], v150 offset:304
	ds_read_b128 v[238:241], v150 offset:320
	ds_read_b128 v[196:199], v150 offset:336
	ds_read_b128 v[200:203], v150 offset:352
	ds_read_b128 v[176:179], v150 offset:368
	v_pk_add_f32 v[180:181], v[180:181], v[242:243]
	v_pk_add_f32 v[174:175], v[174:175], v[172:173]
	v_add_f32_e32 v180, v180, v181
	v_add_f32_e32 v174, v174, v175
	v_add_f32_e32 v180, v127, v180
	v_add_f32_e32 v174, v125, v174
	v_mul_f32_e64 v181, |v180|, s58
	v_mul_f32_e64 v175, |v174|, s58
	v_exp_f32_e32 v181, v181
	v_exp_f32_e32 v175, v175
	v_min_f32_e32 v180, 0, v180
	v_min_f32_e32 v174, 0, v174
	v_add_f32_e32 v181, 1.0, v181
	v_add_f32_e32 v175, 1.0, v175
	v_log_f32_e32 v181, v181
	v_log_f32_e32 v175, v175
	s_nop 0
	v_fma_f32 v152, v180, s82, -v181
	v_fma_f32 v160, v174, s82, -v175
	s_waitcnt lgkmcnt(0)
	v_pk_mul_f32 v[180:181], v[222:223], v[88:89]
	v_pk_mul_f32 v[174:175], v[238:239], v[84:85]
	v_pk_mul_f32 v[242:243], v[224:225], v[90:91]
	v_pk_mul_f32 v[172:173], v[240:241], v[86:87]
	v_pk_fma_f32 v[180:181], v[226:227], v[78:79], v[180:181]
	v_pk_fma_f32 v[174:175], v[196:197], v[58:59], v[174:175]
	v_pk_fma_f32 v[242:243], v[228:229], v[80:81], v[242:243]
	v_pk_fma_f32 v[172:173], v[198:199], v[82:83], v[172:173]
	v_pk_fma_f32 v[180:181], v[230:231], v[54:55], v[180:181]
	v_pk_fma_f32 v[174:175], v[200:201], v[50:51], v[174:175]
	v_pk_fma_f32 v[242:243], v[232:233], v[56:57], v[242:243]
	v_pk_fma_f32 v[172:173], v[202:203], v[52:53], v[172:173]
	v_pk_fma_f32 v[180:181], v[234:235], v[44:45], v[180:181]
	v_pk_fma_f32 v[174:175], v[176:177], v[2:3], v[174:175]
	v_pk_fma_f32 v[242:243], v[236:237], v[46:47], v[242:243]
	v_pk_fma_f32 v[172:173], v[178:179], v[48:49], v[172:173]
	ds_read_b128 v[222:225], v150 offset:384
	ds_read_b128 v[226:229], v150 offset:400
	ds_read_b128 v[230:233], v150 offset:416
	ds_read_b128 v[234:237], v150 offset:432
	ds_read_b128 v[238:241], v150 offset:448
	ds_read_b128 v[196:199], v150 offset:464
	ds_read_b128 v[200:203], v150 offset:480
	ds_read_b128 v[176:179], v150 offset:496
	v_pk_add_f32 v[180:181], v[180:181], v[242:243]
	v_pk_add_f32 v[174:175], v[174:175], v[172:173]
	v_add_f32_e32 v180, v180, v181
	v_add_f32_e32 v174, v174, v175
	v_add_f32_e32 v180, v127, v180
	v_add_f32_e32 v174, v125, v174
	v_mul_f32_e64 v181, |v180|, s58
	v_mul_f32_e64 v175, |v174|, s58
	v_exp_f32_e32 v181, v181
	v_exp_f32_e32 v175, v175
	v_min_f32_e32 v180, 0, v180
	v_min_f32_e32 v174, 0, v174
	v_add_f32_e32 v181, 1.0, v181
	v_add_f32_e32 v175, 1.0, v175
	v_log_f32_e32 v181, v181
	v_log_f32_e32 v175, v175
	s_nop 0
	v_fma_f32 v153, v180, s82, -v181
	v_fma_f32 v161, v174, s82, -v175
	s_waitcnt lgkmcnt(0)
	v_pk_mul_f32 v[180:181], v[222:223], v[88:89]
	v_pk_mul_f32 v[174:175], v[238:239], v[84:85]
	v_pk_mul_f32 v[242:243], v[224:225], v[90:91]
	v_pk_mul_f32 v[172:173], v[240:241], v[86:87]
	v_pk_fma_f32 v[180:181], v[226:227], v[78:79], v[180:181]
	v_pk_fma_f32 v[174:175], v[196:197], v[58:59], v[174:175]
	v_pk_fma_f32 v[242:243], v[228:229], v[80:81], v[242:243]
	v_pk_fma_f32 v[172:173], v[198:199], v[82:83], v[172:173]
	v_pk_fma_f32 v[180:181], v[230:231], v[54:55], v[180:181]
	v_pk_fma_f32 v[174:175], v[200:201], v[50:51], v[174:175]
	v_pk_fma_f32 v[242:243], v[232:233], v[56:57], v[242:243]
	v_pk_fma_f32 v[172:173], v[202:203], v[52:53], v[172:173]
	v_pk_fma_f32 v[180:181], v[234:235], v[44:45], v[180:181]
	v_pk_fma_f32 v[174:175], v[176:177], v[2:3], v[174:175]
	v_pk_fma_f32 v[242:243], v[236:237], v[46:47], v[242:243]
	v_pk_fma_f32 v[172:173], v[178:179], v[48:49], v[172:173]
	ds_read_b128 v[222:225], v150 offset:512
	ds_read_b128 v[226:229], v150 offset:528
	ds_read_b128 v[230:233], v150 offset:544
	ds_read_b128 v[234:237], v150 offset:560
	ds_read_b128 v[238:241], v150 offset:576
	ds_read_b128 v[196:199], v150 offset:592
	ds_read_b128 v[200:203], v150 offset:608
	ds_read_b128 v[176:179], v150 offset:624
	v_pk_add_f32 v[180:181], v[180:181], v[242:243]
	v_pk_add_f32 v[174:175], v[174:175], v[172:173]
	v_add_f32_e32 v180, v180, v181
	v_add_f32_e32 v174, v174, v175
	v_add_f32_e32 v180, v127, v180
	v_add_f32_e32 v174, v125, v174
	v_mul_f32_e64 v181, |v180|, s58
	v_mul_f32_e64 v175, |v174|, s58
	v_exp_f32_e32 v181, v181
	v_exp_f32_e32 v175, v175
	v_min_f32_e32 v180, 0, v180
	v_min_f32_e32 v174, 0, v174
	v_add_f32_e32 v181, 1.0, v181
	v_add_f32_e32 v175, 1.0, v175
	v_log_f32_e32 v181, v181
	v_log_f32_e32 v175, v175
	s_nop 0
	v_fma_f32 v154, v180, s82, -v181
	v_fma_f32 v162, v174, s82, -v175
	s_waitcnt lgkmcnt(0)
	v_pk_mul_f32 v[180:181], v[222:223], v[88:89]
	v_pk_mul_f32 v[174:175], v[238:239], v[84:85]
	v_pk_mul_f32 v[242:243], v[224:225], v[90:91]
	v_pk_mul_f32 v[172:173], v[240:241], v[86:87]
	v_pk_fma_f32 v[180:181], v[226:227], v[78:79], v[180:181]
	v_pk_fma_f32 v[174:175], v[196:197], v[58:59], v[174:175]
	v_pk_fma_f32 v[242:243], v[228:229], v[80:81], v[242:243]
	v_pk_fma_f32 v[172:173], v[198:199], v[82:83], v[172:173]
	v_pk_fma_f32 v[180:181], v[230:231], v[54:55], v[180:181]
	v_pk_fma_f32 v[174:175], v[200:201], v[50:51], v[174:175]
	v_pk_fma_f32 v[242:243], v[232:233], v[56:57], v[242:243]
	v_pk_fma_f32 v[172:173], v[202:203], v[52:53], v[172:173]
	v_pk_fma_f32 v[180:181], v[234:235], v[44:45], v[180:181]
	v_pk_fma_f32 v[174:175], v[176:177], v[2:3], v[174:175]
	v_pk_fma_f32 v[242:243], v[236:237], v[46:47], v[242:243]
	v_pk_fma_f32 v[172:173], v[178:179], v[48:49], v[172:173]
	ds_read_b128 v[222:225], v150 offset:640
	ds_read_b128 v[226:229], v150 offset:656
	ds_read_b128 v[230:233], v150 offset:672
	ds_read_b128 v[234:237], v150 offset:688
	ds_read_b128 v[238:241], v150 offset:704
	ds_read_b128 v[196:199], v150 offset:720
	ds_read_b128 v[200:203], v150 offset:736
	ds_read_b128 v[176:179], v150 offset:752
	v_pk_add_f32 v[180:181], v[180:181], v[242:243]
	v_pk_add_f32 v[174:175], v[174:175], v[172:173]
	v_add_f32_e32 v180, v180, v181
	v_add_f32_e32 v174, v174, v175
	v_add_f32_e32 v180, v127, v180
	v_add_f32_e32 v174, v125, v174
	v_mul_f32_e64 v181, |v180|, s58
	v_mul_f32_e64 v175, |v174|, s58
	v_exp_f32_e32 v181, v181
	v_exp_f32_e32 v175, v175
	v_min_f32_e32 v180, 0, v180
	v_min_f32_e32 v174, 0, v174
	v_add_f32_e32 v181, 1.0, v181
	v_add_f32_e32 v175, 1.0, v175
	v_log_f32_e32 v181, v181
	v_log_f32_e32 v175, v175
	s_nop 0
	v_fma_f32 v155, v180, s82, -v181
	v_fma_f32 v163, v174, s82, -v175
	s_waitcnt lgkmcnt(0)
	v_pk_mul_f32 v[180:181], v[222:223], v[88:89]
	v_pk_mul_f32 v[174:175], v[238:239], v[84:85]
	v_pk_mul_f32 v[242:243], v[224:225], v[90:91]
	v_pk_mul_f32 v[172:173], v[240:241], v[86:87]
	v_pk_fma_f32 v[180:181], v[226:227], v[78:79], v[180:181]
	v_pk_fma_f32 v[174:175], v[196:197], v[58:59], v[174:175]
	v_pk_fma_f32 v[242:243], v[228:229], v[80:81], v[242:243]
	v_pk_fma_f32 v[172:173], v[198:199], v[82:83], v[172:173]
	v_pk_fma_f32 v[180:181], v[230:231], v[54:55], v[180:181]
	v_pk_fma_f32 v[174:175], v[200:201], v[50:51], v[174:175]
	v_pk_fma_f32 v[242:243], v[232:233], v[56:57], v[242:243]
	v_pk_fma_f32 v[172:173], v[202:203], v[52:53], v[172:173]
	v_pk_fma_f32 v[180:181], v[234:235], v[44:45], v[180:181]
	v_pk_fma_f32 v[174:175], v[176:177], v[2:3], v[174:175]
	v_pk_fma_f32 v[242:243], v[236:237], v[46:47], v[242:243]
	v_pk_fma_f32 v[172:173], v[178:179], v[48:49], v[172:173]
	ds_read_b128 v[222:225], v150 offset:768
	ds_read_b128 v[226:229], v150 offset:784
	ds_read_b128 v[230:233], v150 offset:800
	ds_read_b128 v[234:237], v150 offset:816
	ds_read_b128 v[238:241], v150 offset:832
	ds_read_b128 v[196:199], v150 offset:848
	ds_read_b128 v[200:203], v150 offset:864
	ds_read_b128 v[176:179], v150 offset:880
	v_pk_add_f32 v[180:181], v[180:181], v[242:243]
	v_pk_add_f32 v[174:175], v[174:175], v[172:173]
	v_add_f32_e32 v180, v180, v181
	v_add_f32_e32 v174, v174, v175
	v_add_f32_e32 v180, v127, v180
	v_add_f32_e32 v174, v125, v174
	v_mul_f32_e64 v181, |v180|, s58
	v_mul_f32_e64 v175, |v174|, s58
	v_exp_f32_e32 v181, v181
	v_exp_f32_e32 v175, v175
	v_min_f32_e32 v180, 0, v180
	v_min_f32_e32 v174, 0, v174
	v_add_f32_e32 v181, 1.0, v181
	v_add_f32_e32 v175, 1.0, v175
	v_log_f32_e32 v181, v181
	v_log_f32_e32 v175, v175
	s_nop 0
	v_fma_f32 v156, v180, s82, -v181
	v_fma_f32 v164, v174, s82, -v175
	s_waitcnt lgkmcnt(0)
	v_pk_mul_f32 v[180:181], v[222:223], v[88:89]
	v_pk_mul_f32 v[174:175], v[238:239], v[84:85]
	v_pk_mul_f32 v[242:243], v[224:225], v[90:91]
	v_pk_mul_f32 v[172:173], v[240:241], v[86:87]
	v_pk_fma_f32 v[180:181], v[226:227], v[78:79], v[180:181]
	v_pk_fma_f32 v[174:175], v[196:197], v[58:59], v[174:175]
	v_pk_fma_f32 v[242:243], v[228:229], v[80:81], v[242:243]
	v_pk_fma_f32 v[172:173], v[198:199], v[82:83], v[172:173]
	v_pk_fma_f32 v[180:181], v[230:231], v[54:55], v[180:181]
	v_pk_fma_f32 v[174:175], v[200:201], v[50:51], v[174:175]
	v_pk_fma_f32 v[242:243], v[232:233], v[56:57], v[242:243]
	v_pk_fma_f32 v[172:173], v[202:203], v[52:53], v[172:173]
	v_pk_fma_f32 v[180:181], v[234:235], v[44:45], v[180:181]
	v_pk_fma_f32 v[174:175], v[176:177], v[2:3], v[174:175]
	v_pk_fma_f32 v[242:243], v[236:237], v[46:47], v[242:243]
	v_pk_fma_f32 v[172:173], v[178:179], v[48:49], v[172:173]
	ds_read_b128 v[222:225], v150 offset:896
	ds_read_b128 v[226:229], v150 offset:912
	ds_read_b128 v[230:233], v150 offset:928
	ds_read_b128 v[234:237], v150 offset:944
	ds_read_b128 v[238:241], v150 offset:960
	ds_read_b128 v[196:199], v150 offset:976
	ds_read_b128 v[200:203], v150 offset:992
	ds_read_b128 v[176:179], v150 offset:1008
	v_pk_add_f32 v[180:181], v[180:181], v[242:243]
	v_pk_add_f32 v[174:175], v[174:175], v[172:173]
	v_add_f32_e32 v180, v180, v181
	v_add_f32_e32 v174, v174, v175
	v_add_f32_e32 v180, v127, v180
	v_add_f32_e32 v174, v125, v174
	v_mul_f32_e64 v181, |v180|, s58
	v_mul_f32_e64 v175, |v174|, s58
	v_exp_f32_e32 v181, v181
	v_exp_f32_e32 v175, v175
	v_min_f32_e32 v180, 0, v180
	v_min_f32_e32 v174, 0, v174
	v_add_f32_e32 v181, 1.0, v181
	v_add_f32_e32 v175, 1.0, v175
	v_log_f32_e32 v181, v181
	v_log_f32_e32 v175, v175
	s_nop 0
	v_fma_f32 v157, v180, s82, -v181
	v_fma_f32 v165, v174, s82, -v175
	s_waitcnt lgkmcnt(0)
	v_pk_mul_f32 v[180:181], v[222:223], v[88:89]
	v_pk_mul_f32 v[174:175], v[238:239], v[84:85]
	v_pk_mul_f32 v[242:243], v[224:225], v[90:91]
	v_pk_mul_f32 v[172:173], v[240:241], v[86:87]
	v_pk_fma_f32 v[180:181], v[226:227], v[78:79], v[180:181]
	v_pk_fma_f32 v[174:175], v[196:197], v[58:59], v[174:175]
	v_pk_fma_f32 v[242:243], v[228:229], v[80:81], v[242:243]
	v_pk_fma_f32 v[172:173], v[198:199], v[82:83], v[172:173]
	v_pk_fma_f32 v[180:181], v[230:231], v[54:55], v[180:181]
	v_pk_fma_f32 v[174:175], v[200:201], v[50:51], v[174:175]
	v_pk_fma_f32 v[242:243], v[232:233], v[56:57], v[242:243]
	v_pk_fma_f32 v[172:173], v[202:203], v[52:53], v[172:173]
	v_pk_fma_f32 v[180:181], v[234:235], v[44:45], v[180:181]
	v_pk_fma_f32 v[174:175], v[176:177], v[2:3], v[174:175]
	v_pk_fma_f32 v[242:243], v[236:237], v[46:47], v[242:243]
	v_pk_fma_f32 v[172:173], v[178:179], v[48:49], v[172:173]
	v_pk_add_f32 v[180:181], v[180:181], v[242:243]
	v_pk_add_f32 v[174:175], v[174:175], v[172:173]
	v_add_f32_e32 v180, v180, v181
	v_add_f32_e32 v174, v174, v175
	v_add_f32_e32 v180, v127, v180
	v_add_f32_e32 v174, v125, v174
	v_mul_f32_e64 v181, |v180|, s58
	v_mul_f32_e64 v175, |v174|, s58
	v_exp_f32_e32 v181, v181
	v_exp_f32_e32 v175, v175
	v_min_f32_e32 v180, 0, v180
	v_min_f32_e32 v174, 0, v174
	v_add_f32_e32 v181, 1.0, v181
	v_add_f32_e32 v175, 1.0, v175
	v_log_f32_e32 v181, v181
	v_log_f32_e32 v175, v175
	s_nop 0
	v_fma_f32 v158, v180, s82, -v181
	v_fma_f32 v166, v174, s82, -v175
	v_fma_f32 v46, v151, s8, 0
	v_fma_f32 v54, v166, s8, 0
	v_fmamk_f32 v47, v152, 0x3d800000, v46
	v_fmamk_f32 v55, v165, 0x3d800000, v54
	v_fmamk_f32 v48, v153, 0x3d800000, v47
	v_fmamk_f32 v56, v164, 0x3d800000, v55
	v_fmamk_f32 v49, v154, 0x3d800000, v48
	v_fmamk_f32 v57, v163, 0x3d800000, v56
	v_fmamk_f32 v50, v155, 0x3d800000, v49
	v_fmamk_f32 v58, v162, 0x3d800000, v57
	v_fmamk_f32 v51, v156, 0x3d800000, v50
	v_fmamk_f32 v59, v161, 0x3d800000, v58
	v_fmamk_f32 v52, v157, 0x3d800000, v51
	v_fmamk_f32 v78, v160, 0x3d800000, v59
	v_fmamk_f32 v53, v158, 0x3d800000, v52
	v_fmamk_f32 v79, v159, 0x3d800000, v78
	v_add_u32_e32 v2, s7, v149
	ds_write2st64_b32 v2, v53, v79 offset0:64 offset1:72
	s_waitcnt lgkmcnt(0)
	s_barrier
	ds_read2st64_b32 v[2:3], v148 offset0:64 offset1:65
	ds_read2st64_b32 v[44:45], v148 offset0:72 offset1:73
	v_readlane_b32 s8, v245, 52
	s_waitcnt lgkmcnt(0)
	v_add_f32_e32 v2, 0, v2
	v_cndmask_b32_e32 v2, 0, v2, vcc
	s_cselect_b64 vcc, -1, 0
	v_add_f32_e32 v44, 0, v44
	s_cmp_gt_i32 s6, 1
	v_cndmask_b32_e32 v44, 0, v44, vcc
	s_cselect_b64 vcc, -1, 0
	v_add_f32_e32 v3, v2, v3
	s_cmp_lt_i32 s6, 1
	v_cndmask_b32_e32 v80, v2, v3, vcc
	s_cselect_b64 vcc, -1, 0
	v_add_f32_e32 v2, v44, v45
	v_cndmask_b32_e32 v81, 0, v2, vcc
	ds_read2st64_b32 v[2:3], v148 offset0:66 offset1:67
	ds_read2st64_b32 v[44:45], v148 offset0:74 offset1:75
	s_cmp_gt_i32 s6, 2
	s_cselect_b64 vcc, -1, 0
	s_cmp_lt_i32 s6, 2
	s_waitcnt lgkmcnt(0)
	v_add_f32_e32 v2, v80, v2
	v_cndmask_b32_e32 v2, v80, v2, vcc
	s_cselect_b64 vcc, -1, 0
	v_add_f32_e32 v44, v81, v44
	s_cmp_gt_i32 s6, 3
	v_cndmask_b32_e32 v44, 0, v44, vcc
	s_cselect_b64 vcc, -1, 0
	v_add_f32_e32 v3, v2, v3
	s_cmp_lt_i32 s6, 3
	v_cndmask_b32_e32 v80, v2, v3, vcc
	s_cselect_b64 vcc, -1, 0
	v_add_f32_e32 v2, v44, v45
	v_cndmask_b32_e32 v81, 0, v2, vcc
	ds_read2st64_b32 v[2:3], v148 offset0:68 offset1:69
	ds_read2st64_b32 v[44:45], v148 offset0:76 offset1:77
	s_cmp_gt_i32 s6, 4
	s_cselect_b64 vcc, -1, 0
	s_cmp_lt_i32 s6, 4
	s_waitcnt lgkmcnt(0)
	v_add_f32_e32 v2, v80, v2
	v_cndmask_b32_e32 v2, v80, v2, vcc
	s_cselect_b64 vcc, -1, 0
	v_add_f32_e32 v44, v81, v44
	s_cmp_gt_i32 s6, 5
	v_cndmask_b32_e32 v44, 0, v44, vcc
	s_cselect_b64 vcc, -1, 0
	v_add_f32_e32 v3, v2, v3
	s_cmp_lt_i32 s6, 5
	v_cndmask_b32_e32 v80, v2, v3, vcc
	s_cselect_b64 vcc, -1, 0
	v_add_f32_e32 v2, v44, v45
	v_cndmask_b32_e32 v81, 0, v2, vcc
	ds_read2st64_b32 v[2:3], v148 offset0:70 offset1:71
	ds_read2st64_b32 v[44:45], v148 offset0:78 offset1:79
	s_cmp_gt_i32 s6, 6
	s_cselect_b64 vcc, -1, 0
	s_cmp_lt_i32 s6, 6
	s_waitcnt lgkmcnt(0)
	v_add_f32_e32 v2, v80, v2
	v_cndmask_b32_e32 v2, v80, v2, vcc
	s_cselect_b64 vcc, -1, 0
	v_add_f32_e32 v44, v81, v44
	s_cmp_gt_i32 s6, 7
	v_cndmask_b32_e32 v44, 0, v44, vcc
	s_cselect_b64 vcc, -1, 0
	v_add_f32_e32 v3, v2, v3
	s_cmp_lt_i32 s6, 7
	v_cndmask_b32_e32 v2, v2, v3, vcc
	s_cselect_b64 vcc, -1, 0
	v_add_f32_e32 v3, v44, v45
	v_cndmask_b32_e32 v3, 0, v3, vcc
	v_add_f32_e32 v44, v46, v2
	v_add_f32_e32 v45, v79, v3
	v_add_f32_e32 v46, v47, v2
	v_add_f32_e32 v47, v78, v3
	v_add_f32_e32 v48, v48, v2
	v_add_f32_e32 v59, v59, v3
	v_add_f32_e32 v49, v49, v2
	v_add_f32_e32 v58, v58, v3
	v_add_f32_e32 v50, v50, v2
	v_add_f32_e32 v57, v57, v3
	v_add_f32_e32 v51, v51, v2
	v_add_f32_e32 v56, v56, v3
	v_add_f32_e32 v52, v52, v2
	v_add_f32_e32 v55, v55, v3
	v_add_f32_e32 v53, v53, v2
	v_add_f32_e32 v2, v54, v3
	v_exp_f32_e32 v3, v44
	v_exp_f32_e64 v44, -v44
	v_exp_f32_e32 v54, v45
	v_mul_f32_e32 v78, 0x3e000000, v147
	v_mul_f32_e32 v3, v78, v3
	s_mul_i32 s6, s28, 0x240
	v_cvt_pk_bf16_f32 v79, v3, s0
	v_or_b32_e32 v3, s6, v124
	v_mul_f32_e32 v44, v44, v146
	v_lshl_add_u32 v3, v3, 1, 0
	v_cvt_pk_bf16_f32 v44, v44, s0
	ds_write_b16 v3, v44 offset:40960
	v_mul_f32_e32 v44, v78, v54
	v_cvt_pk_bf16_f32 v44, v44, s0
	ds_write_b16 v3, v44 offset:31744
	v_exp_f32_e64 v44, -v45
	v_mul_f32_e32 v54, 0x3e000000, v141
	v_exp_f32_e32 v45, v47
	s_cmpk_lt_u32 s27, 0x100
	v_mul_f32_e32 v44, v44, v146
	v_cvt_pk_bf16_f32 v44, v44, s0
	ds_write_b16 v3, v44 offset:50176
	v_exp_f32_e32 v44, v46
	s_cselect_b64 s[36:37], -1, 0
	s_and_b64 s[6:7], s[36:37], exec
	v_readlane_b32 s6, v245, 49
	v_mul_f32_e32 v44, v54, v44
	v_cvt_pk_bf16_f32 v44, v44, s0
	ds_write_b16 v3, v44 offset:22672
	v_exp_f32_e64 v44, -v46
	v_mul_f32_e32 v46, 0x3e000000, v139
	v_readlane_b32 s7, v245, 50
	s_cselect_b32 s6, s6, s7
	v_mul_f32_e32 v44, v44, v140
	v_cvt_pk_bf16_f32 v44, v44, s0
	ds_write_b16 v3, v44 offset:41104
	v_mul_f32_e32 v44, v54, v45
	v_cvt_pk_bf16_f32 v44, v44, s0
	ds_write_b16 v3, v44 offset:31888
	v_exp_f32_e64 v44, -v47
	v_exp_f32_e32 v45, v59
	v_readlane_b32 s7, v245, 51
	s_cselect_b32 s7, s7, s8
	v_mul_f32_e32 v44, v44, v140
	v_cvt_pk_bf16_f32 v44, v44, s0
	ds_write_b16 v3, v44 offset:50320
	v_exp_f32_e32 v44, v48
	s_and_b32 s29, s28, 3
	ds_write_b16 v3, v79 offset:22528
	s_lshl_b32 s35, s29, 4
	v_mul_f32_e32 v44, v46, v44
	v_cvt_pk_bf16_f32 v44, v44, s0
	ds_write_b16 v3, v44 offset:22816
	v_exp_f32_e64 v44, -v48
	s_cmp_eq_u32 s29, 0
	s_cselect_b64 s[8:9], -1, 0
	s_cmp_lg_u32 s29, 0
	v_mul_f32_e32 v44, v44, v138
	v_cvt_pk_bf16_f32 v44, v44, s0
	ds_write_b16 v3, v44 offset:41248
	v_mul_f32_e32 v44, v46, v45
	v_cvt_pk_bf16_f32 v44, v44, s0
	ds_write_b16 v3, v44 offset:32032
	v_exp_f32_e64 v44, -v59
	v_mul_f32_e32 v46, 0x3e000000, v137
	v_exp_f32_e32 v45, v58
	v_mov_b32_e32 v47, 0
	v_mul_f32_e32 v44, v44, v138
	v_cvt_pk_bf16_f32 v44, v44, s0
	ds_write_b16 v3, v44 offset:50464
	v_exp_f32_e32 v44, v49
	s_nop 0
	v_mul_f32_e32 v44, v46, v44
	v_cvt_pk_bf16_f32 v44, v44, s0
	ds_write_b16 v3, v44 offset:22960
	v_exp_f32_e64 v44, -v49
	s_nop 0
	v_mul_f32_e32 v44, v44, v136
	v_cvt_pk_bf16_f32 v44, v44, s0
	ds_write_b16 v3, v44 offset:41392
	v_mul_f32_e32 v44, v46, v45
	v_cvt_pk_bf16_f32 v44, v44, s0
	ds_write_b16 v3, v44 offset:32176
	v_exp_f32_e64 v44, -v58
	v_mul_f32_e32 v46, 0x3e000000, v135
	v_exp_f32_e32 v45, v57
	v_mul_f32_e32 v44, v44, v136
	v_cvt_pk_bf16_f32 v44, v44, s0
	ds_write_b16 v3, v44 offset:50608
	v_exp_f32_e32 v44, v50
	s_nop 0
	v_mul_f32_e32 v44, v46, v44
	v_cvt_pk_bf16_f32 v44, v44, s0
	ds_write_b16 v3, v44 offset:23104
	v_exp_f32_e64 v44, -v50
	s_nop 0
	v_mul_f32_e32 v44, v44, v134
	v_cvt_pk_bf16_f32 v44, v44, s0
	ds_write_b16 v3, v44 offset:41536
	v_mul_f32_e32 v44, v46, v45
	v_cvt_pk_bf16_f32 v44, v44, s0
	ds_write_b16 v3, v44 offset:32320
	v_exp_f32_e64 v44, -v57
	v_mul_f32_e32 v46, 0x3e000000, v133
	v_exp_f32_e32 v45, v56
	v_mul_f32_e32 v44, v44, v134
	v_cvt_pk_bf16_f32 v44, v44, s0
	ds_write_b16 v3, v44 offset:50752
	v_exp_f32_e32 v44, v51
	s_nop 0
	v_mul_f32_e32 v44, v46, v44
	v_cvt_pk_bf16_f32 v44, v44, s0
	ds_write_b16 v3, v44 offset:23248
	v_exp_f32_e64 v44, -v51
	s_nop 0
	v_mul_f32_e32 v44, v44, v132
	v_cvt_pk_bf16_f32 v44, v44, s0
	ds_write_b16 v3, v44 offset:41680
	v_mul_f32_e32 v44, v46, v45
	v_cvt_pk_bf16_f32 v44, v44, s0
	ds_write_b16 v3, v44 offset:32464
	v_exp_f32_e64 v44, -v56
	v_mul_f32_e32 v46, 0x3e000000, v131
	v_exp_f32_e32 v45, v55
	v_mul_f32_e32 v44, v44, v132
	v_cvt_pk_bf16_f32 v44, v44, s0
	ds_write_b16 v3, v44 offset:50896
	v_exp_f32_e32 v44, v52
	s_nop 0
	v_mul_f32_e32 v44, v46, v44
	v_cvt_pk_bf16_f32 v44, v44, s0
	ds_write_b16 v3, v44 offset:23392
	v_exp_f32_e64 v44, -v52
	s_nop 0
	v_mul_f32_e32 v44, v44, v130
	v_cvt_pk_bf16_f32 v44, v44, s0
	ds_write_b16 v3, v44 offset:41824
	v_mul_f32_e32 v44, v46, v45
	v_cvt_pk_bf16_f32 v44, v44, s0
	ds_write_b16 v3, v44 offset:32608
	v_exp_f32_e64 v44, -v55
	v_mul_f32_e32 v46, 0x3e000000, v129
	v_exp_f32_e32 v45, v2
	v_exp_f32_e64 v2, -v2
	v_mul_f32_e32 v44, v44, v130
	v_cvt_pk_bf16_f32 v44, v44, s0
	ds_write_b16 v3, v44 offset:51040
	v_exp_f32_e32 v44, v53
	v_mul_f32_e32 v2, v2, v128
	v_cvt_pk_bf16_f32 v2, v2, s0
	ds_write_b16 v3, v2 offset:51184
	v_mul_f32_e32 v44, v46, v44
	v_cvt_pk_bf16_f32 v44, v44, s0
	ds_write_b16 v3, v44 offset:23536
	v_exp_f32_e64 v44, -v53
	v_or_b32_e32 v2, s35, v123
	v_mul_u32_u24_e32 v2, 0x90, v2
	v_mul_f32_e32 v44, v44, v128
	v_cvt_pk_bf16_f32 v44, v44, s0
	ds_write_b16 v3, v44 offset:41968
	v_mul_f32_e32 v44, v46, v45
	v_cvt_pk_bf16_f32 v44, v44, s0
	ds_write_b16 v3, v44 offset:32752
	v_lshrrev_b32_e32 v3, 1, v126
	v_and_b32_e32 v3, 24, v3
	v_lshlrev_b32_e32 v3, 1, v3
	v_add3_u32 v50, s6, v2, v3
	v_add_u32_e32 v2, s7, v3
	s_cselect_b64 s[6:7], -1, 0
	s_or_b64 s[10:11], s[36:37], s[8:9]
	s_andn2_b64 vcc, exec, s[10:11]
	s_movk_i32 s10, 0x90
	v_mov_b32_e32 v44, 0
	v_mad_u32_u24 v51, v123, s10, v2
	v_mov_b32_e32 v45, 0
	v_mov_b32_e32 v46, 0
	s_waitcnt lgkmcnt(0)
	s_barrier
	s_cbranch_vccnz .LBB0_190
	ds_read_b128 v[44:47], v50
	ds_read_b128 v[52:55], v51
	s_waitcnt lgkmcnt(0)
	v_mfma_f32_16x16x32_bf16 v[44:47], v[44:47], v[52:55], 0
	ds_read_b128 v[52:55], v50 offset:64
	ds_read_b128 v[56:59], v51 offset:64
	s_waitcnt lgkmcnt(0)
	v_mfma_f32_16x16x32_bf16 v[44:47], v[52:55], v[56:59], v[44:47]

.LBB0_369:
	v_mov_b32_e32 v62, v204
	v_mov_b32_e32 v30, v204
	s_ashr_i32 s4, s6, 2
	s_mul_hi_i32 s5, s4, 0x78787879
	v_lshl_add_u32 v0, v30, 4, 0
	v_lshlrev_b32_e32 v26, 16, v12
	v_and_b32_e32 v27, 0xffff0000, v12
	v_lshlrev_b32_e32 v28, 16, v13
	v_and_b32_e32 v29, 0xffff0000, v13
	v_mad_u64_u32 v[12:13], s[22:23], v30, -12, v[0:1]
	s_lshr_b32 s6, s5, 31
	s_ashr_i32 s5, s5, 5
	ds_write_b128 v0, v[26:29]
	ds_write2st64_b32 v12, v22, v25 offset0:32 offset1:40
	ds_write2st64_b32 v12, v24, v23 offset0:48 offset1:56
	v_ashrrev_i32_e32 v12, 3, v30
	s_add_i32 s5, s5, s6
	v_and_b32_e32 v0, 0x7f, v30
	v_lshlrev_b32_e32 v12, 1, v12
	s_mul_i32 s6, s5, 0x44
	v_readfirstlane_b32 s7, v30
	v_mul_u32_u24_e32 v0, 0x90, v0
	v_and_b32_e32 v12, 0xffffffe0, v12
	s_sub_i32 s4, s4, s6
	s_ashr_i32 s6, s7, 6
	v_add3_u32 v0, s92, v0, v12
	ds_write_b128 v0, v[2:5]
	ds_write_b128 v0, v[6:9] offset:16
	v_lshlrev_b32_e32 v2, 2, v30
	s_lshl_b32 s22, s6, 10
	v_and_b32_e32 v71, 0xfc, v2
	s_add_i32 s22, s22, 0
	v_add_u32_e32 v70, 0, v71
	v_mov_b32_e32 v72, s22
	v_lshlrev_b32_e32 v69, 16, v21
	v_lshlrev_b32_e32 v68, 16, v20
	v_lshlrev_b32_e32 v67, 16, v19
	v_lshlrev_b32_e32 v66, 16, v18
	v_lshlrev_b32_e32 v65, 16, v17
	v_lshlrev_b32_e32 v64, 16, v16
	v_lshlrev_b32_e32 v63, 16, v15
	v_lshlrev_b32_e32 v0, 16, v14
	s_waitcnt lgkmcnt(0)
	s_barrier
	ds_read2st64_b32 v[28:29], v70 offset0:32 offset1:33
	ds_read2st64_b32 v[30:31], v70 offset0:34 offset1:35
	ds_read2st64_b32 v[26:27], v70 offset0:36 offset1:37
	ds_read2st64_b32 v[24:25], v70 offset0:38 offset1:39
	ds_read2st64_b32 v[34:35], v70 offset0:48 offset1:49
	ds_read2st64_b32 v[32:33], v70 offset0:50 offset1:51
	ds_read2st64_b32 v[22:23], v70 offset0:52 offset1:53
	ds_read2st64_b32 v[20:21], v70 offset0:54 offset1:55
	ds_read2st64_b32 v[12:13], v70 offset0:40 offset1:41
	ds_read2st64_b32 v[14:15], v70 offset0:42 offset1:43
	ds_read2st64_b32 v[8:9], v70 offset0:44 offset1:45
	ds_read2st64_b32 v[6:7], v70 offset0:46 offset1:47
	ds_read2st64_b32 v[18:19], v70 offset0:56 offset1:57
	ds_read2st64_b32 v[16:17], v70 offset0:58 offset1:59
	ds_read2st64_b32 v[4:5], v70 offset0:60 offset1:61
	ds_read2st64_b32 v[2:3], v70 offset0:62 offset1:63
	s_mov_b32 s22, 0x3d800000
	s_and_b32 s7, s7, 0x3fffffc0
	s_lshl_b32 s7, s7, 2
	v_readfirstlane_b32 s11, v62
	s_add_i32 s7, s7, 0
	s_ashr_i32 s10, s11, 6
	s_cmp_gt_i32 s6, 0
	s_cselect_b64 vcc, -1, 0
	ds_read_b128 v[100:103], v72
	ds_read_b128 v[104:107], v72 offset:16
	ds_read_b128 v[108:111], v72 offset:32
	ds_read_b128 v[112:115], v72 offset:48
	ds_read_b128 v[116:119], v72 offset:64
	ds_read_b128 v[120:123], v72 offset:80
	ds_read_b128 v[124:127], v72 offset:96
	ds_read_b128 v[128:131], v72 offset:112
	ds_read_b128 v[132:135], v72 offset:128
	ds_read_b128 v[136:139], v72 offset:144
	ds_read_b128 v[146:149], v72 offset:160
	ds_read_b128 v[150:153], v72 offset:176
	ds_read_b128 v[154:157], v72 offset:192
	ds_read_b128 v[158:161], v72 offset:208
	ds_read_b128 v[162:165], v72 offset:224
	ds_read_b128 v[166:169], v72 offset:240
	s_waitcnt lgkmcnt(0)
	v_pk_mul_f32 v[90:91], v[100:101], v[28:29]
	v_pk_mul_f32 v[92:93], v[116:117], v[34:35]
	v_pk_mul_f32 v[94:95], v[132:133], v[28:29]
	v_pk_mul_f32 v[96:97], v[154:155], v[34:35]
	v_pk_fma_f32 v[90:91], v[102:103], v[30:31], v[90:91]
	v_pk_fma_f32 v[92:93], v[118:119], v[32:33], v[92:93]
	v_pk_fma_f32 v[94:95], v[134:135], v[30:31], v[94:95]
	v_pk_fma_f32 v[96:97], v[156:157], v[32:33], v[96:97]
	v_pk_fma_f32 v[90:91], v[104:105], v[26:27], v[90:91]
	v_pk_fma_f32 v[92:93], v[120:121], v[22:23], v[92:93]
	v_pk_fma_f32 v[94:95], v[136:137], v[26:27], v[94:95]
	v_pk_fma_f32 v[96:97], v[158:159], v[22:23], v[96:97]
	v_pk_fma_f32 v[90:91], v[106:107], v[24:25], v[90:91]
	v_pk_fma_f32 v[92:93], v[122:123], v[20:21], v[92:93]
	v_pk_fma_f32 v[94:95], v[138:139], v[24:25], v[94:95]
	v_pk_fma_f32 v[96:97], v[160:161], v[20:21], v[96:97]
	v_pk_fma_f32 v[90:91], v[108:109], v[12:13], v[90:91]
	v_pk_fma_f32 v[92:93], v[124:125], v[18:19], v[92:93]
	v_pk_fma_f32 v[94:95], v[146:147], v[12:13], v[94:95]
	v_pk_fma_f32 v[96:97], v[162:163], v[18:19], v[96:97]
	v_pk_fma_f32 v[90:91], v[110:111], v[14:15], v[90:91]
	v_pk_fma_f32 v[92:93], v[126:127], v[16:17], v[92:93]
	v_pk_fma_f32 v[94:95], v[148:149], v[14:15], v[94:95]
	v_pk_fma_f32 v[96:97], v[164:165], v[16:17], v[96:97]
	v_pk_fma_f32 v[90:91], v[112:113], v[8:9], v[90:91]
	v_pk_fma_f32 v[92:93], v[128:129], v[4:5], v[92:93]
	v_pk_fma_f32 v[94:95], v[150:151], v[8:9], v[94:95]
	v_pk_fma_f32 v[96:97], v[166:167], v[4:5], v[96:97]
	v_pk_fma_f32 v[90:91], v[114:115], v[6:7], v[90:91]
	v_pk_fma_f32 v[92:93], v[130:131], v[2:3], v[92:93]
	v_pk_fma_f32 v[94:95], v[152:153], v[6:7], v[94:95]
	v_pk_fma_f32 v[96:97], v[168:169], v[2:3], v[96:97]
	ds_read_b128 v[100:103], v72 offset:256
	ds_read_b128 v[104:107], v72 offset:272
	ds_read_b128 v[108:111], v72 offset:288
	ds_read_b128 v[112:115], v72 offset:304
	ds_read_b128 v[116:119], v72 offset:320
	ds_read_b128 v[120:123], v72 offset:336
	ds_read_b128 v[124:127], v72 offset:352
	ds_read_b128 v[128:131], v72 offset:368
	ds_read_b128 v[132:135], v72 offset:384
	ds_read_b128 v[136:139], v72 offset:400
	ds_read_b128 v[146:149], v72 offset:416
	ds_read_b128 v[150:153], v72 offset:432
	ds_read_b128 v[154:157], v72 offset:448
	ds_read_b128 v[158:161], v72 offset:464
	ds_read_b128 v[162:165], v72 offset:480
	ds_read_b128 v[166:169], v72 offset:496
	v_add_f32_e32 v90, v90, v91
	v_add_f32_e32 v92, v92, v93
	v_add_f32_e32 v94, v94, v95
	v_add_f32_e32 v96, v96, v97
	v_add_f32_e32 v90, v61, v90
	v_add_f32_e32 v92, v60, v92
	v_add_f32_e32 v94, v61, v94
	v_add_f32_e32 v96, v60, v96
	v_mul_f32_e64 v91, |v90|, s58
	v_mul_f32_e64 v93, |v92|, s58
	v_mul_f32_e64 v95, |v94|, s58
	v_mul_f32_e64 v97, |v96|, s58
	v_exp_f32_e32 v91, v91
	v_exp_f32_e32 v93, v93
	v_exp_f32_e32 v95, v95
	v_exp_f32_e32 v97, v97
	v_add_f32_e32 v91, 1.0, v91
	v_add_f32_e32 v93, 1.0, v93
	v_add_f32_e32 v95, 1.0, v95
	v_add_f32_e32 v97, 1.0, v97
	v_log_f32_e32 v91, v91
	v_log_f32_e32 v93, v93
	v_log_f32_e32 v95, v95
	v_log_f32_e32 v97, v97
	v_min_f32_e32 v90, 0, v90
	v_min_f32_e32 v92, 0, v92
	v_min_f32_e32 v94, 0, v94
	v_min_f32_e32 v96, 0, v96
	v_fma_f32 v73, v90, s82, -v91
	v_fma_f32 v81, v92, s82, -v93
	v_fma_f32 v74, v94, s82, -v95
	v_fma_f32 v82, v96, s82, -v97
	s_waitcnt lgkmcnt(0)
	v_pk_mul_f32 v[90:91], v[100:101], v[28:29]
	v_pk_mul_f32 v[92:93], v[116:117], v[34:35]
	v_pk_mul_f32 v[94:95], v[132:133], v[28:29]
	v_pk_mul_f32 v[96:97], v[154:155], v[34:35]
	v_pk_fma_f32 v[90:91], v[102:103], v[30:31], v[90:91]
	v_pk_fma_f32 v[92:93], v[118:119], v[32:33], v[92:93]
	v_pk_fma_f32 v[94:95], v[134:135], v[30:31], v[94:95]
	v_pk_fma_f32 v[96:97], v[156:157], v[32:33], v[96:97]
	v_pk_fma_f32 v[90:91], v[104:105], v[26:27], v[90:91]
	v_pk_fma_f32 v[92:93], v[120:121], v[22:23], v[92:93]
	v_pk_fma_f32 v[94:95], v[136:137], v[26:27], v[94:95]
	v_pk_fma_f32 v[96:97], v[158:159], v[22:23], v[96:97]
	v_pk_fma_f32 v[90:91], v[106:107], v[24:25], v[90:91]
	v_pk_fma_f32 v[92:93], v[122:123], v[20:21], v[92:93]
	v_pk_fma_f32 v[94:95], v[138:139], v[24:25], v[94:95]
	v_pk_fma_f32 v[96:97], v[160:161], v[20:21], v[96:97]
	v_pk_fma_f32 v[90:91], v[108:109], v[12:13], v[90:91]
	v_pk_fma_f32 v[92:93], v[124:125], v[18:19], v[92:93]
	v_pk_fma_f32 v[94:95], v[146:147], v[12:13], v[94:95]
	v_pk_fma_f32 v[96:97], v[162:163], v[18:19], v[96:97]
	v_pk_fma_f32 v[90:91], v[110:111], v[14:15], v[90:91]
	v_pk_fma_f32 v[92:93], v[126:127], v[16:17], v[92:93]
	v_pk_fma_f32 v[94:95], v[148:149], v[14:15], v[94:95]
	v_pk_fma_f32 v[96:97], v[164:165], v[16:17], v[96:97]
	v_pk_fma_f32 v[90:91], v[112:113], v[8:9], v[90:91]
	v_pk_fma_f32 v[92:93], v[128:129], v[4:5], v[92:93]
	v_pk_fma_f32 v[94:95], v[150:151], v[8:9], v[94:95]
	v_pk_fma_f32 v[96:97], v[166:167], v[4:5], v[96:97]
	v_pk_fma_f32 v[90:91], v[114:115], v[6:7], v[90:91]
	v_pk_fma_f32 v[92:93], v[130:131], v[2:3], v[92:93]
	v_pk_fma_f32 v[94:95], v[152:153], v[6:7], v[94:95]
	v_pk_fma_f32 v[96:97], v[168:169], v[2:3], v[96:97]
	ds_read_b128 v[100:103], v72 offset:512
	ds_read_b128 v[104:107], v72 offset:528
	ds_read_b128 v[108:111], v72 offset:544
	ds_read_b128 v[112:115], v72 offset:560
	ds_read_b128 v[116:119], v72 offset:576
	ds_read_b128 v[120:123], v72 offset:592
	ds_read_b128 v[124:127], v72 offset:608
	ds_read_b128 v[128:131], v72 offset:624
	ds_read_b128 v[132:135], v72 offset:640
	ds_read_b128 v[136:139], v72 offset:656
	ds_read_b128 v[146:149], v72 offset:672
	ds_read_b128 v[150:153], v72 offset:688
	ds_read_b128 v[154:157], v72 offset:704
	ds_read_b128 v[158:161], v72 offset:720
	ds_read_b128 v[162:165], v72 offset:736
	ds_read_b128 v[166:169], v72 offset:752
	v_add_f32_e32 v90, v90, v91
	v_add_f32_e32 v92, v92, v93
	v_add_f32_e32 v94, v94, v95
	v_add_f32_e32 v96, v96, v97
	v_add_f32_e32 v90, v61, v90
	v_add_f32_e32 v92, v60, v92
	v_add_f32_e32 v94, v61, v94
	v_add_f32_e32 v96, v60, v96
	v_mul_f32_e64 v91, |v90|, s58
	v_mul_f32_e64 v93, |v92|, s58
	v_mul_f32_e64 v95, |v94|, s58
	v_mul_f32_e64 v97, |v96|, s58
	v_exp_f32_e32 v91, v91
	v_exp_f32_e32 v93, v93
	v_exp_f32_e32 v95, v95
	v_exp_f32_e32 v97, v97
	v_add_f32_e32 v91, 1.0, v91
	v_add_f32_e32 v93, 1.0, v93
	v_add_f32_e32 v95, 1.0, v95
	v_add_f32_e32 v97, 1.0, v97
	v_log_f32_e32 v91, v91
	v_log_f32_e32 v93, v93
	v_log_f32_e32 v95, v95
	v_log_f32_e32 v97, v97
	v_min_f32_e32 v90, 0, v90
	v_min_f32_e32 v92, 0, v92
	v_min_f32_e32 v94, 0, v94
	v_min_f32_e32 v96, 0, v96
	v_fma_f32 v75, v90, s82, -v91
	v_fma_f32 v83, v92, s82, -v93
	v_fma_f32 v76, v94, s82, -v95
	v_fma_f32 v84, v96, s82, -v97
	s_waitcnt lgkmcnt(0)
	v_pk_mul_f32 v[90:91], v[100:101], v[28:29]
	v_pk_mul_f32 v[92:93], v[116:117], v[34:35]
	v_pk_mul_f32 v[94:95], v[132:133], v[28:29]
	v_pk_mul_f32 v[96:97], v[154:155], v[34:35]
	v_pk_fma_f32 v[90:91], v[102:103], v[30:31], v[90:91]
	v_pk_fma_f32 v[92:93], v[118:119], v[32:33], v[92:93]
	v_pk_fma_f32 v[94:95], v[134:135], v[30:31], v[94:95]
	v_pk_fma_f32 v[96:97], v[156:157], v[32:33], v[96:97]
	v_pk_fma_f32 v[90:91], v[104:105], v[26:27], v[90:91]
	v_pk_fma_f32 v[92:93], v[120:121], v[22:23], v[92:93]
	v_pk_fma_f32 v[94:95], v[136:137], v[26:27], v[94:95]
	v_pk_fma_f32 v[96:97], v[158:159], v[22:23], v[96:97]
	v_pk_fma_f32 v[90:91], v[106:107], v[24:25], v[90:91]
	v_pk_fma_f32 v[92:93], v[122:123], v[20:21], v[92:93]
	v_pk_fma_f32 v[94:95], v[138:139], v[24:25], v[94:95]
	v_pk_fma_f32 v[96:97], v[160:161], v[20:21], v[96:97]
	v_pk_fma_f32 v[90:91], v[108:109], v[12:13], v[90:91]
	v_pk_fma_f32 v[92:93], v[124:125], v[18:19], v[92:93]
	v_pk_fma_f32 v[94:95], v[146:147], v[12:13], v[94:95]
	v_pk_fma_f32 v[96:97], v[162:163], v[18:19], v[96:97]
	v_pk_fma_f32 v[90:91], v[110:111], v[14:15], v[90:91]
	v_pk_fma_f32 v[92:93], v[126:127], v[16:17], v[92:93]
	v_pk_fma_f32 v[94:95], v[148:149], v[14:15], v[94:95]
	v_pk_fma_f32 v[96:97], v[164:165], v[16:17], v[96:97]
	v_pk_fma_f32 v[90:91], v[112:113], v[8:9], v[90:91]
	v_pk_fma_f32 v[92:93], v[128:129], v[4:5], v[92:93]
	v_pk_fma_f32 v[94:95], v[150:151], v[8:9], v[94:95]
	v_pk_fma_f32 v[96:97], v[166:167], v[4:5], v[96:97]
	v_pk_fma_f32 v[90:91], v[114:115], v[6:7], v[90:91]
	v_pk_fma_f32 v[92:93], v[130:131], v[2:3], v[92:93]
	v_pk_fma_f32 v[94:95], v[152:153], v[6:7], v[94:95]
	v_pk_fma_f32 v[96:97], v[168:169], v[2:3], v[96:97]
	ds_read_b128 v[100:103], v72 offset:768
	ds_read_b128 v[104:107], v72 offset:784
	ds_read_b128 v[108:111], v72 offset:800
	ds_read_b128 v[112:115], v72 offset:816
	ds_read_b128 v[116:119], v72 offset:832
	ds_read_b128 v[120:123], v72 offset:848
	ds_read_b128 v[124:127], v72 offset:864
	ds_read_b128 v[128:131], v72 offset:880
	ds_read_b128 v[132:135], v72 offset:896
	ds_read_b128 v[136:139], v72 offset:912
	ds_read_b128 v[146:149], v72 offset:928
	ds_read_b128 v[150:153], v72 offset:944
	ds_read_b128 v[154:157], v72 offset:960
	ds_read_b128 v[158:161], v72 offset:976
	ds_read_b128 v[162:165], v72 offset:992
	ds_read_b128 v[166:169], v72 offset:1008
	v_add_f32_e32 v90, v90, v91
	v_add_f32_e32 v92, v92, v93
	v_add_f32_e32 v94, v94, v95
	v_add_f32_e32 v96, v96, v97
	v_add_f32_e32 v90, v61, v90
	v_add_f32_e32 v92, v60, v92
	v_add_f32_e32 v94, v61, v94
	v_add_f32_e32 v96, v60, v96
	v_mul_f32_e64 v91, |v90|, s58
	v_mul_f32_e64 v93, |v92|, s58
	v_mul_f32_e64 v95, |v94|, s58
	v_mul_f32_e64 v97, |v96|, s58
	v_exp_f32_e32 v91, v91
	v_exp_f32_e32 v93, v93
	v_exp_f32_e32 v95, v95
	v_exp_f32_e32 v97, v97
	v_add_f32_e32 v91, 1.0, v91
	v_add_f32_e32 v93, 1.0, v93
	v_add_f32_e32 v95, 1.0, v95
	v_add_f32_e32 v97, 1.0, v97
	v_log_f32_e32 v91, v91
	v_log_f32_e32 v93, v93
	v_log_f32_e32 v95, v95
	v_log_f32_e32 v97, v97
	v_min_f32_e32 v90, 0, v90
	v_min_f32_e32 v92, 0, v92
	v_min_f32_e32 v94, 0, v94
	v_min_f32_e32 v96, 0, v96
	v_fma_f32 v77, v90, s82, -v91
	v_fma_f32 v85, v92, s82, -v93
	v_fma_f32 v78, v94, s82, -v95
	v_fma_f32 v86, v96, s82, -v97
	s_waitcnt lgkmcnt(0)
	v_pk_mul_f32 v[90:91], v[100:101], v[28:29]
	v_pk_mul_f32 v[92:93], v[116:117], v[34:35]
	v_pk_mul_f32 v[94:95], v[132:133], v[28:29]
	v_pk_mul_f32 v[96:97], v[154:155], v[34:35]
	v_pk_fma_f32 v[90:91], v[102:103], v[30:31], v[90:91]
	v_pk_fma_f32 v[92:93], v[118:119], v[32:33], v[92:93]
	v_pk_fma_f32 v[94:95], v[134:135], v[30:31], v[94:95]
	v_pk_fma_f32 v[96:97], v[156:157], v[32:33], v[96:97]
	v_pk_fma_f32 v[90:91], v[104:105], v[26:27], v[90:91]
	v_pk_fma_f32 v[92:93], v[120:121], v[22:23], v[92:93]
	v_pk_fma_f32 v[94:95], v[136:137], v[26:27], v[94:95]
	v_pk_fma_f32 v[96:97], v[158:159], v[22:23], v[96:97]
	v_pk_fma_f32 v[90:91], v[106:107], v[24:25], v[90:91]
	v_pk_fma_f32 v[92:93], v[122:123], v[20:21], v[92:93]
	v_pk_fma_f32 v[94:95], v[138:139], v[24:25], v[94:95]
	v_pk_fma_f32 v[96:97], v[160:161], v[20:21], v[96:97]
	v_pk_fma_f32 v[90:91], v[108:109], v[12:13], v[90:91]
	v_pk_fma_f32 v[92:93], v[124:125], v[18:19], v[92:93]
	v_pk_fma_f32 v[94:95], v[146:147], v[12:13], v[94:95]
	v_pk_fma_f32 v[96:97], v[162:163], v[18:19], v[96:97]
	v_pk_fma_f32 v[90:91], v[110:111], v[14:15], v[90:91]
	v_pk_fma_f32 v[92:93], v[126:127], v[16:17], v[92:93]
	v_pk_fma_f32 v[94:95], v[148:149], v[14:15], v[94:95]
	v_pk_fma_f32 v[96:97], v[164:165], v[16:17], v[96:97]
	v_pk_fma_f32 v[90:91], v[112:113], v[8:9], v[90:91]
	v_pk_fma_f32 v[92:93], v[128:129], v[4:5], v[92:93]
	v_pk_fma_f32 v[94:95], v[150:151], v[8:9], v[94:95]
	v_pk_fma_f32 v[96:97], v[166:167], v[4:5], v[96:97]
	v_pk_fma_f32 v[90:91], v[114:115], v[6:7], v[90:91]
	v_pk_fma_f32 v[92:93], v[130:131], v[2:3], v[92:93]
	v_pk_fma_f32 v[94:95], v[152:153], v[6:7], v[94:95]
	v_pk_fma_f32 v[96:97], v[168:169], v[2:3], v[96:97]
	v_add_f32_e32 v90, v90, v91
	v_add_f32_e32 v92, v92, v93
	v_add_f32_e32 v94, v94, v95
	v_add_f32_e32 v96, v96, v97
	v_add_f32_e32 v90, v61, v90
	v_add_f32_e32 v92, v60, v92
	v_add_f32_e32 v94, v61, v94
	v_add_f32_e32 v96, v60, v96
	v_mul_f32_e64 v91, |v90|, s58
	v_mul_f32_e64 v93, |v92|, s58
	v_mul_f32_e64 v95, |v94|, s58
	v_mul_f32_e64 v97, |v96|, s58
	v_exp_f32_e32 v91, v91
	v_exp_f32_e32 v93, v93
	v_exp_f32_e32 v95, v95
	v_exp_f32_e32 v97, v97
	v_add_f32_e32 v91, 1.0, v91
	v_add_f32_e32 v93, 1.0, v93
	v_add_f32_e32 v95, 1.0, v95
	v_add_f32_e32 v97, 1.0, v97
	v_log_f32_e32 v91, v91
	v_log_f32_e32 v93, v93
	v_log_f32_e32 v95, v95
	v_log_f32_e32 v97, v97
	v_min_f32_e32 v90, 0, v90
	v_min_f32_e32 v92, 0, v92
	v_min_f32_e32 v94, 0, v94
	v_min_f32_e32 v96, 0, v96
	v_fma_f32 v79, v90, s82, -v91
	v_fma_f32 v87, v92, s82, -v93
	v_fma_f32 v80, v94, s82, -v95
	v_fma_f32 v88, v96, s82, -v97
	v_fma_f32 v20, v73, s22, 0
	v_fma_f32 v28, v88, s22, 0
	v_fmamk_f32 v21, v74, 0x3d800000, v20
	v_fmamk_f32 v29, v87, 0x3d800000, v28
	v_fmamk_f32 v22, v75, 0x3d800000, v21
	v_fmamk_f32 v30, v86, 0x3d800000, v29
	v_fmamk_f32 v23, v76, 0x3d800000, v22
	v_fmamk_f32 v31, v85, 0x3d800000, v30
	v_fmamk_f32 v24, v77, 0x3d800000, v23
	v_fmamk_f32 v32, v84, 0x3d800000, v31
	v_fmamk_f32 v25, v78, 0x3d800000, v24
	v_fmamk_f32 v33, v83, 0x3d800000, v32
	v_fmamk_f32 v26, v79, 0x3d800000, v25
	v_fmamk_f32 v34, v82, 0x3d800000, v33
	v_fmamk_f32 v27, v80, 0x3d800000, v26
	v_fmamk_f32 v35, v81, 0x3d800000, v34
	v_add_u32_e32 v2, s7, v71
	ds_write2st64_b32 v2, v27, v35 offset0:64 offset1:72
	s_waitcnt lgkmcnt(0)
	s_barrier
	ds_read2st64_b32 v[2:3], v70 offset0:64 offset1:65
	ds_read2st64_b32 v[4:5], v70 offset0:72 offset1:73
	ds_read2st64_b32 v[6:7], v70 offset0:66 offset1:67
	ds_read2st64_b32 v[8:9], v70 offset0:68 offset1:69
	ds_read2st64_b32 v[12:13], v70 offset0:70 offset1:71
	s_waitcnt lgkmcnt(0)
	v_add_f32_e32 v2, 0, v2
	s_cmp_lt_i32 s6, 0
	v_cndmask_b32_e32 v60, 0, v2, vcc
	s_waitcnt lgkmcnt(3)
	v_add_f32_e32 v4, 0, v4
	s_cselect_b64 vcc, -1, 0
	s_cmp_gt_i32 s6, 1
	ds_read2st64_b32 v[14:15], v70 offset0:74 offset1:75
	ds_read2st64_b32 v[16:17], v70 offset0:76 offset1:77
	ds_read2st64_b32 v[18:19], v70 offset0:78 offset1:79
	v_cndmask_b32_e32 v61, 0, v4, vcc
	v_add_f32_e32 v2, v2, v3
	v_add_f32_e32 v3, v60, v3
	s_cselect_b64 vcc, -1, 0
	s_cmp_lt_i32 s6, 1
	v_cndmask_b32_e32 v3, v60, v3, vcc
	v_add_f32_e32 v60, v61, v5
	s_cselect_b64 vcc, -1, 0
	s_cmp_gt_i32 s6, 2
	v_cndmask_b32_e32 v60, 0, v60, vcc
	s_waitcnt lgkmcnt(5)
	v_add_f32_e32 v2, v2, v6
	v_add_f32_e32 v6, v3, v6
	s_cselect_b64 vcc, -1, 0
	s_cmp_lt_i32 s6, 2
	v_cndmask_b32_e32 v3, v3, v6, vcc
	s_waitcnt lgkmcnt(0)
	v_add_f32_e32 v6, v60, v14
	s_cselect_b64 vcc, -1, 0
	s_cmp_gt_i32 s6, 3
	v_cndmask_b32_e32 v6, 0, v6, vcc
	v_add_f32_e32 v2, v2, v7
	v_add_f32_e32 v7, v3, v7
	s_cselect_b64 vcc, -1, 0
	s_cmp_lt_i32 s6, 3
	v_cndmask_b32_e32 v3, v3, v7, vcc
	v_add_f32_e32 v6, v6, v15
	s_cselect_b64 vcc, -1, 0
	s_cmp_gt_i32 s6, 4
	v_cndmask_b32_e32 v6, 0, v6, vcc
	v_add_f32_e32 v7, v3, v8
	s_cselect_b64 vcc, -1, 0
	s_cmp_lt_i32 s6, 4
	v_cndmask_b32_e32 v3, v3, v7, vcc
	s_waitcnt lgkmcnt(1)
	v_add_f32_e32 v6, v6, v16
	s_cselect_b64 vcc, -1, 0
	s_cmp_gt_i32 s6, 5
	v_cndmask_b32_e32 v6, 0, v6, vcc
	v_add_f32_e32 v7, v3, v9
	s_cselect_b64 vcc, -1, 0
	s_cmp_lt_i32 s6, 5
	v_cndmask_b32_e32 v3, v3, v7, vcc
	v_add_f32_e32 v6, v6, v17
	s_cselect_b64 vcc, -1, 0
	s_cmp_gt_i32 s6, 6
	v_cndmask_b32_e32 v6, 0, v6, vcc
	v_add_f32_e32 v7, v3, v12
	s_cselect_b64 vcc, -1, 0
	s_cmp_lt_i32 s6, 6
	v_add_f32_e32 v2, v2, v8
	v_cndmask_b32_e32 v3, v3, v7, vcc
	s_waitcnt lgkmcnt(0)
	v_add_f32_e32 v6, v6, v18
	s_cselect_b64 vcc, -1, 0
	s_cmp_gt_i32 s6, 7
	v_add_f32_e32 v2, v2, v9
	v_cndmask_b32_e32 v6, 0, v6, vcc
	v_add_f32_e32 v7, v3, v13
	s_cselect_b64 vcc, -1, 0
	v_add_f32_e32 v2, v2, v12
	v_cndmask_b32_e32 v3, v3, v7, vcc
	v_add_f32_e32 v2, v2, v13
	v_add_f32_e32 v7, v20, v3
	v_add_f32_e32 v9, v21, v3
	v_add_f32_e32 v13, v22, v3
	v_add_f32_e32 v21, v23, v3
	v_add_f32_e32 v23, v24, v3
	v_add_f32_e32 v25, v25, v3
	v_add_f32_e32 v26, v26, v3
	v_add_f32_e32 v27, v27, v3
	v_add_f32_e32 v3, v4, v5
	v_add_f32_e32 v3, v3, v14
	v_add_f32_e32 v3, v3, v15
	s_cmp_lt_i32 s6, 7
	v_add_f32_e32 v3, v3, v16
	v_add_f32_e32 v6, v6, v19
	s_cselect_b64 vcc, -1, 0
	v_add_f32_e32 v3, v3, v17
	v_cndmask_b32_e32 v6, 0, v6, vcc
	v_add_f32_e32 v3, v3, v18
	v_add_f32_e32 v8, v35, v6
	v_add_f32_e32 v3, v3, v19
	v_sub_f32_e32 v4, v2, v7
	v_sub_f32_e32 v5, v3, v8
	v_sub_f32_e32 v7, v2, v9
	v_exp_f32_e32 v5, v5
	v_exp_f32_e32 v7, v7
	v_add_f32_e32 v12, v34, v6
	v_add_f32_e32 v22, v32, v6
	v_mul_f32_e32 v8, v5, v69
	v_mul_f32_e32 v9, v7, v68
	v_sub_f32_e32 v5, v3, v12
	v_sub_f32_e32 v7, v2, v13
	v_exp_f32_e32 v5, v5
	v_exp_f32_e32 v7, v7
	v_add_f32_e32 v20, v33, v6
	v_add_f32_e32 v30, v30, v6
	v_mul_f32_e32 v15, v5, v68
	v_mul_f32_e32 v5, v7, v67
	v_sub_f32_e32 v7, v3, v22
	v_exp_f32_e32 v7, v7
	v_add_f32_e32 v29, v29, v6
	v_sub_f32_e32 v12, v3, v20
	v_sub_f32_e32 v13, v2, v21
	v_mul_f32_e32 v18, v7, v66
	v_sub_f32_e32 v7, v3, v30
	v_sub_f32_e32 v19, v2, v26
	v_sub_f32_e32 v20, v3, v29
	v_sub_f32_e32 v21, v2, v27
	v_exp_f32_e32 v7, v7
	v_exp_f32_e32 v19, v19
	v_exp_f32_e32 v20, v20
	v_exp_f32_e32 v21, v21
	v_add_f32_e32 v24, v31, v6
	v_add_f32_e32 v6, v28, v6
	v_mul_f32_e32 v22, v7, v64
	v_mul_f32_e32 v7, v19, v63
	v_mul_f32_e32 v19, v20, v63
	v_mul_f32_e32 v20, v21, v0
	v_sub_f32_e32 v6, v3, v6
	v_exp_f32_e32 v12, v12
	v_exp_f32_e32 v13, v13
	v_cvt_pk_bf16_f32 v7, v7, v20
	v_exp_f32_e32 v20, v6
	v_mul_f32_e32 v12, v12, v67
	v_mul_f32_e32 v13, v13, v66
	v_cvt_pk_bf16_f32 v5, v5, v13
	v_mul_f32_e32 v0, v20, v0
	v_cvt_pk_bf16_f32 v13, v12, v18
	v_cvt_pk_bf16_f32 v12, v8, v15
	v_cvt_pk_bf16_f32 v15, v19, v0
	v_and_b32_e32 v0, 63, v62
	s_lshl_b32 s6, s10, 4
	v_mul_u32_u24_e32 v8, 0x48, v0
	s_add_i32 s6, s6, 0
	v_lshl_add_u32 v8, v8, 1, s6
	s_lshl_b32 s5, s5, 3
	s_and_b32 s6, s8, 6
	v_sub_f32_e32 v14, v2, v23
	v_sub_f32_e32 v16, v3, v24
	v_sub_f32_e32 v17, v2, v25
	s_or_b32 s5, s5, s6
	v_exp_f32_e32 v4, v4
	v_exp_f32_e32 v14, v14
	v_exp_f32_e32 v16, v16
	v_exp_f32_e32 v17, v17
	s_mul_hi_i32 s7, s5, 0x44
	s_mulk_i32 s5, 0x44
	s_ashr_i32 s22, s4, 31
	s_add_u32 s6, s5, s4
	s_addc_u32 s7, s7, s22
	s_add_u32 s4, s6, 0x44
	v_mul_f32_e32 v4, v4, v69
	v_mul_f32_e32 v14, v14, v65
	v_mul_f32_e32 v16, v16, v65
	v_mul_f32_e32 v17, v17, v64
	s_addc_u32 s5, s7, 0
	v_cvt_pk_bf16_f32 v6, v14, v17
	v_cvt_pk_bf16_f32 v4, v4, v9
	v_cvt_pk_bf16_f32 v14, v16, v22
	s_cmp_gt_u32 s11, 63
	ds_write_b128 v8, v[4:7] offset:22528
	ds_write_b128 v8, v[12:15] offset:31744
	s_cbranch_scc1 .LBB0_362
	v_mov_b32_e32 v4, s59
	ds_read_b64 v[4:5], v4
	v_exp_f32_e32 v2, v2
	v_lshlrev_b32_e32 v0, 2, v0
	s_waitcnt lgkmcnt(0)
	v_readfirstlane_b32 s22, v4
	v_readfirstlane_b32 s11, v5
	s_add_u32 s26, s22, 0x500000
	s_addc_u32 s11, s11, 0
	s_lshl_b64 s[22:23], s[6:7], 8
	s_add_u32 s22, s26, s22
	s_addc_u32 s23, s11, s23
	v_lshl_add_u64 v[4:5], s[22:23], 0, v[0:1]
	global_store_dword v[4:5], v2, off
	v_exp_f32_e32 v4, v3
	s_lshl_b64 s[22:23], s[4:5], 8
	s_add_u32 s22, s26, s22
	s_addc_u32 s23, s11, s23
	v_lshl_add_u64 v[2:3], s[22:23], 0, v[0:1]
	global_store_dword v[2:3], v4, off
	s_branch .LBB0_362
